# g3: 16 serialized ds_bpermute xor-butterfly row reductions per unit replaced by DPP adds (bitwise identical), on top of the conv-epilogue store merge
# baseline (speedup 1.0000x reference)
; #define LAS __attribute__((address_space(3)))
; __device__ __forceinline__ unsigned pk2(float lo, float hi) { return pg8::cvt_pk_bf16_safe(lo, hi); }
; __device__ __forceinline__ void phase_g3(const Args& a, LAS unsigned char* lds, int tid, int lane, int wave) {
;     ...
;             for (int x = 0; x < 4; ++x) { const int i = 16 * it + 4 * q4 + x, j = 16 * jt + r16; Ps[i * 72 + j] = (bf16)(pk2(j <= i ? sc[x] : 0.f, 0.f) & 0xffffu); } }
;         __syncthreads();
;         f32x4 acc[4][2];
; #pragma unroll
;         for (int mt = 0; mt < 4; ++mt)
; #pragma unroll
;             for (int nt = 0; nt < 2; ++nt) acc[mt][nt] = (f32x4){0.f, 0.f, 0.f, 0.f};
; #pragma unroll
;         for (int ks = 0; ks < 2; ++ks)
; #pragma unroll
;             for (int mt = 0; mt < 4; ++mt) { const bf16x8 af = *(const LAS bf16x8*)(Ps + (16 * mt + r16) * 72 + 32 * ks + 8 * q4);
; #pragma unroll
;                 for (int nt = 0; nt < 2; ++nt) acc[mt][nt] = __builtin_amdgcn_mfma_f32_16x16x32_bf16(af, vf[nt][ks], acc[mt][nt], 0, 0, 0); }
; #pragma unroll
;         for (int ks = 0; ks < 4; ++ks) {
; #pragma unroll
;             for (int mt = 0; mt < 4; ++mt) { const bf16x8 af = *(const LAS bf16x8*)(Qs + (16 * mt + r16) * 136 + 32 * ks + 8 * q4);
; #pragma unroll
;                 for (int nt = 0; nt < 2; ++nt) acc[mt][nt] = __builtin_amdgcn_mfma_f32_16x16x32_bf16(af, sf[ks][nt], acc[mt][nt], 0, 0, 0); } }
; #pragma unroll
;         for (int mt = 0; mt < 4; ++mt)
; #pragma unroll
;             for (int x = 0; x < 4; ++x) { float ss = acc[mt][0][x] * acc[mt][0][x] + acc[mt][1][x] * acc[mt][1][x];
;                 ss += __shfl_xor(ss, 1); ss += __shfl_xor(ss, 2); ss += __shfl_xor(ss, 4); ss += __shfl_xor(ss, 8);
;                 if (r16 == 0) part[wave * 64 + 16 * mt + 4 * q4 + x] = ss; }
.LBB0_433:
	s_nop 7
	v_cvt_pk_bf16_f32 v100, v100, s0
	v_cndmask_b32_e64 v100, v100, 0, s[26:27]
	ds_write_b16 v200, v100 offset:43552
	v_cvt_pk_bf16_f32 v100, v101, s0
	v_cndmask_b32_e64 v100, v100, 0, s[28:29]
	ds_write_b16 v200, v100 offset:43696
	v_cvt_pk_bf16_f32 v100, v102, s0
	v_cndmask_b32_e64 v100, v100, 0, s[30:31]
	ds_write_b16 v200, v100 offset:43840
	v_cvt_pk_bf16_f32 v100, v103, s0
	v_cndmask_b32_e64 v100, v100, 0, s[34:35]
	ds_write_b16 v200, v100 offset:43984
	s_waitcnt lgkmcnt(0)
	s_barrier
	ds_read_b128 v[100:103], v189 offset:43520
	ds_read_b128 v[204:207], v189 offset:43584
	ds_read_b128 v[212:215], v189 offset:45824
	ds_read_b128 v[216:219], v189 offset:45888
	ds_read_b128 v[224:227], v189 offset:48128
	ds_read_b128 v[228:231], v189 offset:48192
	ds_read_b128 v[236:239], v190 offset:43520
	ds_read_b128 v[240:243], v190 offset:43584
	s_waitcnt lgkmcnt(7)
	v_mfma_f32_16x16x32_bf16 v[208:211], v[100:103], v[96:99], 0
	v_mfma_f32_16x16x32_bf16 v[100:103], v[100:103], v[92:95], 0
	s_waitcnt lgkmcnt(5)
	v_mfma_f32_16x16x32_bf16 v[220:223], v[212:215], v[96:99], 0
	v_mfma_f32_16x16x32_bf16 v[212:215], v[212:215], v[92:95], 0
	s_waitcnt lgkmcnt(3)
	v_mfma_f32_16x16x32_bf16 v[232:235], v[224:227], v[96:99], 0
	v_mfma_f32_16x16x32_bf16 v[224:227], v[224:227], v[92:95], 0
	s_waitcnt lgkmcnt(1)
	v_mfma_f32_16x16x32_bf16 v[96:99], v[236:239], v[96:99], 0
	v_mfma_f32_16x16x32_bf16 v[92:95], v[236:239], v[92:95], 0
	v_mfma_f32_16x16x32_bf16 v[208:211], v[204:207], v[88:91], v[208:211]
	v_mfma_f32_16x16x32_bf16 v[100:103], v[204:207], v[84:87], v[100:103]
	v_mfma_f32_16x16x32_bf16 v[204:207], v[216:219], v[88:91], v[220:223]
	v_mfma_f32_16x16x32_bf16 v[212:215], v[216:219], v[84:87], v[212:215]
	v_mfma_f32_16x16x32_bf16 v[216:219], v[228:231], v[88:91], v[232:235]
	v_mfma_f32_16x16x32_bf16 v[220:223], v[228:231], v[84:87], v[224:227]
	s_waitcnt lgkmcnt(0)
	v_mfma_f32_16x16x32_bf16 v[88:91], v[240:243], v[88:91], v[96:99]
	v_mfma_f32_16x16x32_bf16 v[84:87], v[240:243], v[84:87], v[92:95]
	s_nop 2
	ds_read_b128 v[92:95], v191 offset:8704
	ds_read_b128 v[96:99], v191 offset:8768
	s_waitcnt vmcnt(7) lgkmcnt(1)
	v_mfma_f32_16x16x32_bf16 v[208:211], v[92:95], v[76:79], v[208:211]
	s_waitcnt vmcnt(5)
	v_mfma_f32_16x16x32_bf16 v[92:95], v[92:95], v[80:83], v[100:103]
	s_nop 2
	ds_read_b128 v[100:103], v191 offset:13056
	ds_read_b128 v[224:227], v191 offset:13120
	s_waitcnt lgkmcnt(1)
	v_mfma_f32_16x16x32_bf16 v[204:207], v[100:103], v[76:79], v[204:207]
	v_mfma_f32_16x16x32_bf16 v[100:103], v[100:103], v[80:83], v[212:215]
	s_nop 2
	ds_read_b128 v[212:215], v191 offset:17408
	ds_read_b128 v[228:231], v191 offset:17472
	s_waitcnt lgkmcnt(1)
	v_mfma_f32_16x16x32_bf16 v[216:219], v[212:215], v[76:79], v[216:219]
	v_mfma_f32_16x16x32_bf16 v[212:215], v[212:215], v[80:83], v[220:223]
	s_nop 2
	ds_read_b128 v[220:223], v192 offset:8704
	ds_read_b128 v[232:235], v192 offset:8768
	s_waitcnt lgkmcnt(1)
	v_mfma_f32_16x16x32_bf16 v[76:79], v[220:223], v[76:79], v[88:91]
	v_mfma_f32_16x16x32_bf16 v[80:83], v[220:223], v[80:83], v[84:87]
	v_mfma_f32_16x16x32_bf16 v[84:87], v[96:99], v[68:71], v[208:211]
	s_waitcnt vmcnt(4)
	v_mfma_f32_16x16x32_bf16 v[88:91], v[96:99], v[72:75], v[92:95]
	v_mfma_f32_16x16x32_bf16 v[92:95], v[224:227], v[68:71], v[204:207]
	v_mfma_f32_16x16x32_bf16 v[96:99], v[224:227], v[72:75], v[100:103]
	v_mfma_f32_16x16x32_bf16 v[100:103], v[228:231], v[68:71], v[216:219]
	v_mfma_f32_16x16x32_bf16 v[204:207], v[228:231], v[72:75], v[212:215]
	s_waitcnt lgkmcnt(0)
	v_mfma_f32_16x16x32_bf16 v[68:71], v[232:235], v[68:71], v[76:79]
	v_mfma_f32_16x16x32_bf16 v[72:75], v[232:235], v[72:75], v[80:83]
	s_nop 1
	ds_read_b128 v[76:79], v191 offset:8832
	ds_read_b128 v[80:83], v191 offset:8896
	s_waitcnt vmcnt(3) lgkmcnt(1)
	v_mfma_f32_16x16x32_bf16 v[84:87], v[76:79], v[60:63], v[84:87]
	s_waitcnt vmcnt(1)
	v_mfma_f32_16x16x32_bf16 v[76:79], v[76:79], v[64:67], v[88:91]
	s_nop 2
	ds_read_b128 v[88:91], v191 offset:13184
	ds_read_b128 v[208:211], v191 offset:13248
	s_waitcnt lgkmcnt(1)
	v_mfma_f32_16x16x32_bf16 v[92:95], v[88:91], v[60:63], v[92:95]
	v_mfma_f32_16x16x32_bf16 v[88:91], v[88:91], v[64:67], v[96:99]
	s_nop 2
	ds_read_b128 v[96:99], v191 offset:17536
	ds_read_b128 v[212:215], v191 offset:17600
	s_waitcnt lgkmcnt(1)
	v_mfma_f32_16x16x32_bf16 v[100:103], v[96:99], v[60:63], v[100:103]
	v_mfma_f32_16x16x32_bf16 v[96:99], v[96:99], v[64:67], v[204:207]
	s_nop 2
	ds_read_b128 v[204:207], v192 offset:8832
	ds_read_b128 v[216:219], v192 offset:8896
	s_waitcnt lgkmcnt(1)
	v_mfma_f32_16x16x32_bf16 v[220:223], v[204:207], v[60:63], v[68:71]
	v_and_b32_e32 v61, 64, v201
	v_xor_b32_e32 v60, 1, v201
	s_waitcnt vmcnt(0)
	v_mfma_f32_16x16x32_bf16 v[68:71], v[80:83], v[52:55], v[76:79]
	v_mfma_f32_16x16x32_bf16 v[84:87], v[80:83], v[56:59], v[84:87]
	v_mfma_f32_16x16x32_bf16 v[204:207], v[204:207], v[64:67], v[72:75]
	s_nop 2
	v_add_u32_e32 v75, 64, v61
	v_cmp_lt_i32_e32 vcc, v60, v75
	s_nop 0
	v_mul_f32_e32 v61, v68, v68
	v_fmac_f32_e32 v61, v84, v84
	v_cndmask_b32_e32 v60, v201, v60, vcc
	v_lshlrev_b32_e32 v72, 2, v60
	v_xor_b32_e32 v60, 2, v201
	v_cmp_lt_i32_e32 vcc, v60, v75
	v_mfma_f32_16x16x32_bf16 v[64:67], v[208:211], v[52:55], v[88:91]
	s_nop 0
	v_cndmask_b32_e32 v60, v201, v60, vcc
	v_lshlrev_b32_e32 v73, 2, v60
	s_waitcnt lgkmcnt(0)
	s_nop 1
	v_add_f32_dpp v88, v61, v61 quad_perm:[1,0,3,2] row_mask:0xf bank_mask:0xf
	v_xor_b32_e32 v60, 4, v201
	v_cmp_lt_i32_e32 vcc, v60, v75
	v_xor_b32_e32 v90, 8, v201
	v_mfma_f32_16x16x32_bf16 v[80:83], v[208:211], v[56:59], v[92:95]
	v_cndmask_b32_e32 v60, v201, v60, vcc
	v_lshlrev_b32_e32 v74, 2, v60
	s_waitcnt lgkmcnt(0)
	s_nop 1
	v_add_f32_dpp v88, v88, v88 quad_perm:[2,3,0,1] row_mask:0xf bank_mask:0xf
	v_cmp_lt_i32_e32 vcc, v90, v75
	v_mfma_f32_16x16x32_bf16 v[76:79], v[212:215], v[56:59], v[100:103]
	s_waitcnt lgkmcnt(0)
	s_nop 1
	v_add_f32_dpp v88, v88, v88 row_half_mirror row_mask:0xf bank_mask:0xf
	v_cndmask_b32_e32 v75, v201, v90, vcc
	v_lshlrev_b32_e32 v75, 2, v75
	s_nop 1
	v_add_f32_dpp v88, v88, v88 row_mirror row_mask:0xf bank_mask:0xf
	v_mfma_f32_16x16x32_bf16 v[60:63], v[212:215], v[52:55], v[96:99]
	v_mfma_f32_16x16x32_bf16 v[56:59], v[216:219], v[56:59], v[220:223]
	v_mfma_f32_16x16x32_bf16 v[52:55], v[216:219], v[52:55], v[204:207]
	s_and_saveexec_b64 s[38:39], s[14:15]
	s_cbranch_execz .LBB0_435
	s_waitcnt lgkmcnt(0)
	ds_write_b32 v202, v88 offset:6144
; __device__ __forceinline__ void phase_g3(const Args& a, LAS unsigned char* lds, int tid, int lane, int wave) {
;     ...
;         for (int mt = 0; mt < 4; ++mt)
; #pragma unroll
;             for (int x = 0; x < 4; ++x) { float ss = acc[mt][0][x] * acc[mt][0][x] + acc[mt][1][x] * acc[mt][1][x];
;                 ss += __shfl_xor(ss, 1); ss += __shfl_xor(ss, 2); ss += __shfl_xor(ss, 4); ss += __shfl_xor(ss, 8);
;                 if (r16 == 0) part[wave * 64 + 16 * mt + 4 * q4 + x] = ss; }
.LBB0_435:
	s_or_b64 exec, exec, s[38:39]
	v_mul_f32_e32 v88, v69, v69
	v_fmac_f32_e32 v88, v85, v85
	s_waitcnt lgkmcnt(0)
	s_waitcnt lgkmcnt(0)
	s_nop 1
	v_add_f32_dpp v88, v88, v88 quad_perm:[1,0,3,2] row_mask:0xf bank_mask:0xf
	s_waitcnt lgkmcnt(0)
	s_nop 1
	v_add_f32_dpp v88, v88, v88 quad_perm:[2,3,0,1] row_mask:0xf bank_mask:0xf
	s_waitcnt lgkmcnt(0)
	s_nop 1
	v_add_f32_dpp v88, v88, v88 row_half_mirror row_mask:0xf bank_mask:0xf
	s_nop 1
	v_add_f32_dpp v88, v88, v88 row_mirror row_mask:0xf bank_mask:0xf
	s_and_saveexec_b64 s[38:39], s[14:15]
	s_cbranch_execz .LBB0_437
	s_waitcnt lgkmcnt(0)
	ds_write_b32 v202, v88 offset:6148
.LBB0_437:
	s_or_b64 exec, exec, s[38:39]
	v_mul_f32_e32 v88, v70, v70
	v_fmac_f32_e32 v88, v86, v86
	s_waitcnt lgkmcnt(0)
	s_waitcnt lgkmcnt(0)
	s_nop 1
	v_add_f32_dpp v88, v88, v88 quad_perm:[1,0,3,2] row_mask:0xf bank_mask:0xf
	s_waitcnt lgkmcnt(0)
	s_nop 1
	v_add_f32_dpp v88, v88, v88 quad_perm:[2,3,0,1] row_mask:0xf bank_mask:0xf
	s_waitcnt lgkmcnt(0)
	s_nop 1
	v_add_f32_dpp v88, v88, v88 row_half_mirror row_mask:0xf bank_mask:0xf
	s_nop 1
	v_add_f32_dpp v88, v88, v88 row_mirror row_mask:0xf bank_mask:0xf
	s_and_saveexec_b64 s[38:39], s[14:15]
	s_cbranch_execz .LBB0_439
	s_waitcnt lgkmcnt(0)
	ds_write_b32 v202, v88 offset:6152
.LBB0_439:
	s_or_b64 exec, exec, s[38:39]
	v_mul_f32_e32 v88, v71, v71
	v_fmac_f32_e32 v88, v87, v87
	s_waitcnt lgkmcnt(0)
	s_waitcnt lgkmcnt(0)
	s_nop 1
	v_add_f32_dpp v88, v88, v88 quad_perm:[1,0,3,2] row_mask:0xf bank_mask:0xf
	s_waitcnt lgkmcnt(0)
	s_nop 1
	v_add_f32_dpp v88, v88, v88 quad_perm:[2,3,0,1] row_mask:0xf bank_mask:0xf
	s_waitcnt lgkmcnt(0)
	s_nop 1
	v_add_f32_dpp v88, v88, v88 row_half_mirror row_mask:0xf bank_mask:0xf
	s_nop 1
	v_add_f32_dpp v88, v88, v88 row_mirror row_mask:0xf bank_mask:0xf
	s_and_saveexec_b64 s[38:39], s[14:15]
	s_cbranch_execz .LBB0_441
	s_waitcnt lgkmcnt(0)
	ds_write_b32 v202, v88 offset:6156
.LBB0_441:
	s_or_b64 exec, exec, s[38:39]
	v_mul_f32_e32 v88, v64, v64
	v_fmac_f32_e32 v88, v80, v80
	s_waitcnt lgkmcnt(0)
	s_waitcnt lgkmcnt(0)
	s_nop 1
	v_add_f32_dpp v88, v88, v88 quad_perm:[1,0,3,2] row_mask:0xf bank_mask:0xf
	s_waitcnt lgkmcnt(0)
	s_nop 1
	v_add_f32_dpp v88, v88, v88 quad_perm:[2,3,0,1] row_mask:0xf bank_mask:0xf
	s_waitcnt lgkmcnt(0)
	s_nop 1
	v_add_f32_dpp v88, v88, v88 row_half_mirror row_mask:0xf bank_mask:0xf
	s_nop 1
	v_add_f32_dpp v88, v88, v88 row_mirror row_mask:0xf bank_mask:0xf
	s_and_saveexec_b64 s[38:39], s[14:15]
	s_cbranch_execz .LBB0_443
	s_waitcnt lgkmcnt(0)
	ds_write_b32 v202, v88 offset:6208
.LBB0_443:
	s_or_b64 exec, exec, s[38:39]
	v_mul_f32_e32 v88, v65, v65
	v_fmac_f32_e32 v88, v81, v81
	s_waitcnt lgkmcnt(0)
	s_waitcnt lgkmcnt(0)
	s_nop 1
	v_add_f32_dpp v88, v88, v88 quad_perm:[1,0,3,2] row_mask:0xf bank_mask:0xf
	s_waitcnt lgkmcnt(0)
	s_nop 1
	v_add_f32_dpp v88, v88, v88 quad_perm:[2,3,0,1] row_mask:0xf bank_mask:0xf
	s_waitcnt lgkmcnt(0)
	s_nop 1
	v_add_f32_dpp v88, v88, v88 row_half_mirror row_mask:0xf bank_mask:0xf
	s_nop 1
	v_add_f32_dpp v88, v88, v88 row_mirror row_mask:0xf bank_mask:0xf
	s_and_saveexec_b64 s[38:39], s[14:15]
	s_cbranch_execz .LBB0_445
	s_waitcnt lgkmcnt(0)
	ds_write_b32 v202, v88 offset:6212
.LBB0_445:
	s_or_b64 exec, exec, s[38:39]
	v_mul_f32_e32 v88, v66, v66
	v_fmac_f32_e32 v88, v82, v82
	s_waitcnt lgkmcnt(0)
	s_waitcnt lgkmcnt(0)
	s_nop 1
	v_add_f32_dpp v88, v88, v88 quad_perm:[1,0,3,2] row_mask:0xf bank_mask:0xf
	s_waitcnt lgkmcnt(0)
	s_nop 1
	v_add_f32_dpp v88, v88, v88 quad_perm:[2,3,0,1] row_mask:0xf bank_mask:0xf
	s_waitcnt lgkmcnt(0)
	s_nop 1
	v_add_f32_dpp v88, v88, v88 row_half_mirror row_mask:0xf bank_mask:0xf
	s_nop 1
	v_add_f32_dpp v88, v88, v88 row_mirror row_mask:0xf bank_mask:0xf
	s_and_saveexec_b64 s[38:39], s[14:15]
	s_cbranch_execz .LBB0_447
	s_waitcnt lgkmcnt(0)
	ds_write_b32 v202, v88 offset:6216
.LBB0_447:
	s_or_b64 exec, exec, s[38:39]
	v_mul_f32_e32 v88, v67, v67
	v_fmac_f32_e32 v88, v83, v83
	s_waitcnt lgkmcnt(0)
	s_waitcnt lgkmcnt(0)
	s_nop 1
	v_add_f32_dpp v88, v88, v88 quad_perm:[1,0,3,2] row_mask:0xf bank_mask:0xf
	s_waitcnt lgkmcnt(0)
	s_nop 1
	v_add_f32_dpp v88, v88, v88 quad_perm:[2,3,0,1] row_mask:0xf bank_mask:0xf
	s_waitcnt lgkmcnt(0)
	s_nop 1
	v_add_f32_dpp v88, v88, v88 row_half_mirror row_mask:0xf bank_mask:0xf
	s_nop 1
	v_add_f32_dpp v88, v88, v88 row_mirror row_mask:0xf bank_mask:0xf
	s_and_saveexec_b64 s[38:39], s[14:15]
	s_cbranch_execz .LBB0_449
	s_waitcnt lgkmcnt(0)
	ds_write_b32 v202, v88 offset:6220
; __device__ __forceinline__ void phase_g3(const Args& a, LAS unsigned char* lds, int tid, int lane, int wave) {
;     ...
;         for (int mt = 0; mt < 4; ++mt)
; #pragma unroll
;             for (int x = 0; x < 4; ++x) { float ss = acc[mt][0][x] * acc[mt][0][x] + acc[mt][1][x] * acc[mt][1][x];
;                 ss += __shfl_xor(ss, 1); ss += __shfl_xor(ss, 2); ss += __shfl_xor(ss, 4); ss += __shfl_xor(ss, 8);
;                 if (r16 == 0) part[wave * 64 + 16 * mt + 4 * q4 + x] = ss; }
.LBB0_449:
	s_or_b64 exec, exec, s[38:39]
	v_mul_f32_e32 v88, v60, v60
	v_fmac_f32_e32 v88, v76, v76
	s_waitcnt lgkmcnt(0)
	s_waitcnt lgkmcnt(0)
	s_nop 1
	v_add_f32_dpp v88, v88, v88 quad_perm:[1,0,3,2] row_mask:0xf bank_mask:0xf
	s_waitcnt lgkmcnt(0)
	s_nop 1
	v_add_f32_dpp v88, v88, v88 quad_perm:[2,3,0,1] row_mask:0xf bank_mask:0xf
	s_waitcnt lgkmcnt(0)
	s_nop 1
	v_add_f32_dpp v88, v88, v88 row_half_mirror row_mask:0xf bank_mask:0xf
	s_nop 1
	v_add_f32_dpp v88, v88, v88 row_mirror row_mask:0xf bank_mask:0xf
	s_and_saveexec_b64 s[38:39], s[14:15]
	s_cbranch_execz .LBB0_451
	s_waitcnt lgkmcnt(0)
	ds_write_b32 v202, v88 offset:6272
.LBB0_451:
	s_or_b64 exec, exec, s[38:39]
	v_mul_f32_e32 v88, v61, v61
	v_fmac_f32_e32 v88, v77, v77
	s_waitcnt lgkmcnt(0)
	s_waitcnt lgkmcnt(0)
	s_nop 1
	v_add_f32_dpp v88, v88, v88 quad_perm:[1,0,3,2] row_mask:0xf bank_mask:0xf
	s_waitcnt lgkmcnt(0)
	s_nop 1
	v_add_f32_dpp v88, v88, v88 quad_perm:[2,3,0,1] row_mask:0xf bank_mask:0xf
	s_waitcnt lgkmcnt(0)
	s_nop 1
	v_add_f32_dpp v88, v88, v88 row_half_mirror row_mask:0xf bank_mask:0xf
	s_nop 1
	v_add_f32_dpp v88, v88, v88 row_mirror row_mask:0xf bank_mask:0xf
	s_and_saveexec_b64 s[38:39], s[14:15]
	s_cbranch_execz .LBB0_453
	s_waitcnt lgkmcnt(0)
	ds_write_b32 v202, v88 offset:6276
.LBB0_453:
	s_or_b64 exec, exec, s[38:39]
	v_mul_f32_e32 v88, v62, v62
	v_fmac_f32_e32 v88, v78, v78
	s_waitcnt lgkmcnt(0)
	s_waitcnt lgkmcnt(0)
	s_nop 1
	v_add_f32_dpp v88, v88, v88 quad_perm:[1,0,3,2] row_mask:0xf bank_mask:0xf
	s_waitcnt lgkmcnt(0)
	s_nop 1
	v_add_f32_dpp v88, v88, v88 quad_perm:[2,3,0,1] row_mask:0xf bank_mask:0xf
	s_waitcnt lgkmcnt(0)
	s_nop 1
	v_add_f32_dpp v88, v88, v88 row_half_mirror row_mask:0xf bank_mask:0xf
	s_nop 1
	v_add_f32_dpp v88, v88, v88 row_mirror row_mask:0xf bank_mask:0xf
	s_and_saveexec_b64 s[38:39], s[14:15]
	s_cbranch_execz .LBB0_455
	s_waitcnt lgkmcnt(0)
	ds_write_b32 v202, v88 offset:6280
.LBB0_455:
	s_or_b64 exec, exec, s[38:39]
	v_mul_f32_e32 v88, v63, v63
	v_fmac_f32_e32 v88, v79, v79
	s_waitcnt lgkmcnt(0)
	s_waitcnt lgkmcnt(0)
	s_nop 1
	v_add_f32_dpp v88, v88, v88 quad_perm:[1,0,3,2] row_mask:0xf bank_mask:0xf
	s_waitcnt lgkmcnt(0)
	s_nop 1
	v_add_f32_dpp v88, v88, v88 quad_perm:[2,3,0,1] row_mask:0xf bank_mask:0xf
	s_waitcnt lgkmcnt(0)
	s_nop 1
	v_add_f32_dpp v88, v88, v88 row_half_mirror row_mask:0xf bank_mask:0xf
	s_nop 1
	v_add_f32_dpp v88, v88, v88 row_mirror row_mask:0xf bank_mask:0xf
	s_and_saveexec_b64 s[38:39], s[14:15]
	s_cbranch_execz .LBB0_457
	s_waitcnt lgkmcnt(0)
	ds_write_b32 v202, v88 offset:6284
.LBB0_457:
	s_or_b64 exec, exec, s[38:39]
	v_mul_f32_e32 v88, v52, v52
	v_fmac_f32_e32 v88, v56, v56
	s_waitcnt lgkmcnt(0)
	s_waitcnt lgkmcnt(0)
	s_nop 1
	v_add_f32_dpp v88, v88, v88 quad_perm:[1,0,3,2] row_mask:0xf bank_mask:0xf
	s_waitcnt lgkmcnt(0)
	s_nop 1
	v_add_f32_dpp v88, v88, v88 quad_perm:[2,3,0,1] row_mask:0xf bank_mask:0xf
	s_waitcnt lgkmcnt(0)
	s_nop 1
	v_add_f32_dpp v88, v88, v88 row_half_mirror row_mask:0xf bank_mask:0xf
	s_nop 1
	v_add_f32_dpp v88, v88, v88 row_mirror row_mask:0xf bank_mask:0xf
	s_and_saveexec_b64 s[38:39], s[14:15]
	s_cbranch_execz .LBB0_459
	s_waitcnt lgkmcnt(0)
	ds_write_b32 v202, v88 offset:6336
.LBB0_459:
	s_or_b64 exec, exec, s[38:39]
	v_mul_f32_e32 v88, v53, v53
	v_fmac_f32_e32 v88, v57, v57
	s_waitcnt lgkmcnt(0)
	s_waitcnt lgkmcnt(0)
	s_nop 1
	v_add_f32_dpp v88, v88, v88 quad_perm:[1,0,3,2] row_mask:0xf bank_mask:0xf
	s_waitcnt lgkmcnt(0)
	s_nop 1
	v_add_f32_dpp v88, v88, v88 quad_perm:[2,3,0,1] row_mask:0xf bank_mask:0xf
	s_waitcnt lgkmcnt(0)
	s_nop 1
	v_add_f32_dpp v88, v88, v88 row_half_mirror row_mask:0xf bank_mask:0xf
	s_nop 1
	v_add_f32_dpp v88, v88, v88 row_mirror row_mask:0xf bank_mask:0xf
	s_and_saveexec_b64 s[38:39], s[14:15]
	s_cbranch_execz .LBB0_461
	s_waitcnt lgkmcnt(0)
	ds_write_b32 v202, v88 offset:6340
.LBB0_461:
	s_or_b64 exec, exec, s[38:39]
	v_mul_f32_e32 v88, v54, v54
	v_fmac_f32_e32 v88, v58, v58
	s_waitcnt lgkmcnt(0)
	s_waitcnt lgkmcnt(0)
	s_nop 1
	v_add_f32_dpp v88, v88, v88 quad_perm:[1,0,3,2] row_mask:0xf bank_mask:0xf
	s_waitcnt lgkmcnt(0)
	s_nop 1
	v_add_f32_dpp v88, v88, v88 quad_perm:[2,3,0,1] row_mask:0xf bank_mask:0xf
	s_waitcnt lgkmcnt(0)
	s_nop 1
	v_add_f32_dpp v88, v88, v88 row_half_mirror row_mask:0xf bank_mask:0xf
	s_nop 1
	v_add_f32_dpp v88, v88, v88 row_mirror row_mask:0xf bank_mask:0xf
	s_and_saveexec_b64 s[38:39], s[14:15]
	s_cbranch_execz .LBB0_463
	s_waitcnt lgkmcnt(0)
	ds_write_b32 v202, v88 offset:6344
.LBB0_463:
	s_or_b64 exec, exec, s[38:39]
	v_mul_f32_e32 v88, v55, v55
	v_fmac_f32_e32 v88, v59, v59
	s_waitcnt lgkmcnt(0)
	s_nop 1
	v_add_f32_dpp v72, v88, v88 quad_perm:[1,0,3,2] row_mask:0xf bank_mask:0xf
	s_waitcnt lgkmcnt(0)
	s_nop 1
	v_add_f32_dpp v72, v72, v72 quad_perm:[2,3,0,1] row_mask:0xf bank_mask:0xf
	s_waitcnt lgkmcnt(0)
	s_nop 1
	v_add_f32_dpp v72, v72, v72 row_half_mirror row_mask:0xf bank_mask:0xf
	s_nop 1
	v_add_f32_dpp v72, v72, v72 row_mirror row_mask:0xf bank_mask:0xf
	s_and_saveexec_b64 s[38:39], s[14:15]
	s_cbranch_execz .LBB0_465
	s_waitcnt lgkmcnt(0)
	ds_write_b32 v202, v72 offset:6348
